# NSA: selected-branch epilogue loads batched 8-wide; far-tile loop addresses via SGPR bases + invariant lane offsets
# speedup vs baseline: 1.0050x; 1.0050x over previous
; DI int otid() { int z; asm volatile("s_mov_b32 %0, 0" : "=s"(z)); return (int)threadIdx.x + z; }
;   DI float aux(int key) const { return (cuml[key] + cpre[key >> 7]) * LOG2E; }
;           DI float aux(int key) const { int n = key < 511 ? key : 510; return __int_as_float(pos[16 * n + 31]); }
;   DI float aux(int key) const { return __int_as_float(pos[key]); }
;   DI float aux(int key) const { return __int_as_float(pos[key]); }
; template <int DK, bool PV, bool PF, class Ctx>
; DI void attn_run(const bf16x8 (&qf)[DK / 16], f32x16 (&o)[4], float& m, float& l, const bf16* K1, int ldk1,
;                  const bf16* K2, int ldk2, const bf16* Vt, int ldv, int first, Ctx& ctx, char* smem) {
;     ...
;   auto ldk = [&](int i, int key0) -> uint4 {
;     int c = otid() + 256 * i;
;     int row = c / CPR, cc = c % CPR;
;     const bf16* src;
;     if (DK == 128 || cc < 16) src = K1 + (size_t)(key0 + row) * ldk1 + cc * 8;
;     else src = K2 + (size_t)(key0 + row) * ldk2 + (cc - 16) * 8;
;     return *(const uint4*)src;
;   };
;   auto stk = [&](int i, const uint4& v) {
;     int c = tid + 256 * i;
;     int row = c / CPR, cc = c % CPR;
;     *(uint4*)(Ks + row * (DK + 8) + cc * 8) = v;
;   };
;   auto gload = [&](int key0) {
;     rk0 = ldk(0, key0); rk1 = ldk(1, key0); rk2 = ldk(2, key0); rk3 = ldk(3, key0);
;     if (NKC > 4) { rk4 = ldk(4, key0); rk5 = ldk(5, key0); }
;     const int tl = otid();
; #pragma unroll
;     for (int i = 0; i < 4; ++i) {
;       int c = tl + 256 * i;
;       int d = c >> 3, cc = c & 7;
;       rv[i] = *(const uint4*)(Vt + (size_t)d * ldv + key0 + cc * 8);
;     }
;     raux = (tid < 64) ? ctx.aux(key0 + tid) : 0.f;
;   };
;   auto sstore = [&]() {
;     stk(0, rk0); stk(1, rk1); stk(2, rk2); stk(3, rk3);
;     if (NKC > 4) { stk(4, rk4); stk(5, rk5); }
; #pragma unroll
;     for (int i = 0; i < 4; ++i) {
;       int c = tid + 256 * i;
;       int d = c >> 3, cc = c & 7;
;       uint2* dst = (uint2*)(Vs + d * 68 + cc * 8);
;       dst[0] = make_uint2(rv[i].x, rv[i].y);
;       dst[1] = make_uint2(rv[i].z, rv[i].w);
;     }
;     if (tid < 64) ((float*)(smem + AT_AUX))[tid] = raux;
;   };
;   if (PF) gload(tcur * 64);
;   while (tcur >= 0) {
;     __syncthreads();
;     if (!PF) gload(tcur * 64);
;     sstore();
;     __syncthreads();
.LBB0_760:
	s_cmp_lt_i32 s26, 0
	s_mov_b32 s6, 0
	s_cbranch_scc1 .LBB0_776
	v_add_u32_e32 v7, s6, v189
	v_ashrrev_i32_e32 v0, 31, v7
	v_lshrrev_b32_e32 v0, 28, v0
	v_add_u32_e32 v0, v7, v0
	v_lshrrev_b32_e32 v2, 4, v0
	v_and_b32_e32 v0, 0xffffff0, v0
	v_sub_u32_e32 v0, v7, v0
	v_add_u32_e32 v4, 0x100, v7
	v_lshlrev_b32_e32 v9, 4, v0
	v_ashrrev_i32_e32 v0, 31, v4
	v_lshrrev_b32_e32 v0, 28, v0
	v_add_u32_e32 v0, v4, v0
	v_mul_lo_u32 v8, v2, s73
	v_lshrrev_b32_e32 v2, 4, v0
	v_and_b32_e32 v0, 0xffffff0, v0
	v_sub_u32_e32 v0, v4, v0
	v_add_u32_e32 v12, 0x200, v7
	v_lshlrev_b32_e32 v11, 4, v0
	v_ashrrev_i32_e32 v0, 31, v12
	v_lshrrev_b32_e32 v0, 28, v0
	v_add_u32_e32 v0, v12, v0
	v_mul_lo_u32 v10, v2, s73
	v_lshrrev_b32_e32 v2, 4, v0
	v_and_b32_e32 v0, 0xffffff0, v0
	v_sub_u32_e32 v0, v12, v0
	v_add_u32_e32 v80, 0x300, v7
	v_lshlrev_b32_e32 v82, 4, v0
	v_ashrrev_i32_e32 v0, 31, v80
	v_lshrrev_b32_e32 v0, 28, v0
	v_add_u32_e32 v0, v80, v0
	v_mul_lo_u32 v13, v2, s73
	v_lshrrev_b32_e32 v2, 4, v0
	v_and_b32_e32 v0, 0xffffff0, v0
	v_sub_u32_e32 v0, v80, v0
	v_lshlrev_b32_e32 v84, 4, v0
	v_lshlrev_b32_e32 v0, 4, v7
	v_mul_lo_u32 v83, v2, s73
	v_lshrrev_b32_e32 v2, 3, v7
	v_and_b32_e32 v0, 0x70, v0
	v_mad_u64_u32 v[2:3], s[6:7], v2, s68, v[0:1]
	v_lshrrev_b32_e32 v3, 3, v4
	v_mad_u64_u32 v[4:5], s[6:7], v3, s68, v[0:1]
	v_lshrrev_b32_e32 v3, 3, v12
	v_mad_u64_u32 v[14:15], s[6:7], v3, s68, v[0:1]
	v_lshrrev_b32_e32 v3, 3, v80
	v_mad_u64_u32 v[80:81], s[6:7], v3, s68, v[0:1]
	v_cmp_gt_i32_e64 s[10:11], 64, v7
	v_lshlrev_b32_e32 v7, 2, v7
	v_add_u32_e32 v8, v8, v9
	v_add_u32_e32 v9, v10, v11
	v_add_u32_e32 v10, v13, v82
	v_add_u32_e32 v11, v83, v84
	v_add_u32_e32 v12, 0x6400, v2
	v_add_u32_e32 v13, 0x6400, v4
	v_add_u32_e32 v14, 0x6400, v14
	v_add_u32_e32 v15, 0x6400, v80
	v_lshrrev_b32_e32 v196, 4, v189
	v_mul_u32_u24_e32 v196, 0x3500, v196
	v_and_b32_e32 v197, 15, v189
	v_lshl_add_u32 v196, v197, 4, v196
	v_lshrrev_b32_e32 v197, 3, v189
	v_lshlrev_b32_e32 v197, 14, v197
	v_and_b32_e32 v198, 7, v189
	v_lshl_or_b32 v197, v198, 4, v197
.LBB0_762:
	s_waitcnt lgkmcnt(0)
	s_barrier
	s_lshl_b32 s64, s26, 6
	s_mul_i32 s6, s64, s67
	s_add_u32 s6, s42, s6
	s_addc_u32 s7, s43, 0
	global_load_dwordx4 v[2:5], v196, s[6:7]
	s_add_u32 s6, s6, 0x35000
	s_addc_u32 s7, s7, 0
	global_load_dwordx4 v[80:83], v196, s[6:7]
	s_add_u32 s6, s6, 0x35000
	s_addc_u32 s7, s7, 0
	global_load_dwordx4 v[84:87], v196, s[6:7]
	s_add_u32 s6, s6, 0x35000
	s_addc_u32 s7, s7, 0
	global_load_dwordx4 v[88:91], v196, s[6:7]
	s_lshl_b32 s6, s64, 1
	s_add_u32 s6, s0, s6
	s_addc_u32 s7, s1, 0
	global_load_dwordx4 v[100:103], v197, s[6:7]
	s_add_u32 s6, s6, 0x80000
	s_addc_u32 s7, s7, 0
	global_load_dwordx4 v[104:107], v197, s[6:7]
	s_add_u32 s6, s6, 0x80000
	s_addc_u32 s7, s7, 0
	global_load_dwordx4 v[108:111], v197, s[6:7]
	s_add_u32 s6, s6, 0x80000
	s_addc_u32 s7, s7, 0
	s_waitcnt vmcnt(6)
	ds_write_b128 v8, v[2:5]
	global_load_dwordx4 v[2:5], v197, s[6:7]
	s_waitcnt vmcnt(6)
	ds_write_b128 v9, v[80:83]
	s_waitcnt vmcnt(5)
	ds_write_b128 v10, v[84:87]
	s_waitcnt vmcnt(4)
	ds_write_b128 v11, v[88:91]
	s_waitcnt vmcnt(3)
	ds_write2_b64 v12, v[100:101], v[102:103] offset1:1
	s_waitcnt vmcnt(2)
	ds_write2_b64 v13, v[104:105], v[106:107] offset1:1
	s_waitcnt vmcnt(1)
	ds_write2_b64 v14, v[108:109], v[110:111] offset1:1
	s_waitcnt vmcnt(0)
	ds_write2_b64 v15, v[2:3], v[4:5] offset1:1
	s_and_saveexec_b64 s[6:7], s[10:11]
	ds_write_b32 v7, v1 offset:43008
	s_or_b64 exec, exec, s[6:7]
	s_cmpk_gt_u32 s26, 0x7e
	s_mov_b32 s6, -1
	s_waitcnt lgkmcnt(0)
	s_barrier
	s_cbranch_scc1 .LBB0_772
	s_add_i32 s27, s64, 0x7f
	s_mov_b32 s36, s26
	s_branch .LBB0_767

; DI float sigm(float x) { return 1.f / (1.f + __expf(-x)); }
; __global__ void __launch_bounds__(256, LB2) mega(Params p, int ph_lo, int ph_hi) {
;     ...
;           lt = l + __shfl_xor(l, 32);
;           float gs = sigm(GT[(size_t)tq * 24 + head * 3 + 1]) / lt;
; #pragma unroll
;           for (int d = 0; d < 4; ++d)
; #pragma unroll
;             for (int i4 = 0; i4 < 4; ++i4) {
;               int dv0 = d * 32 + 8 * i4 + 4 * h;
;               float4 v = *(float4*)(orow + dv0);
;               v.x += o[d][4 * i4] * gs; v.y += o[d][4 * i4 + 1] * gs; v.z += o[d][4 * i4 + 2] * gs; v.w += o[d][4 * i4 + 3] * gs;
;               *(float4*)(orow + dv0) = v;
;             }
.LBB0_776:
	global_load_dword v0, v[158:159], off offset:4
	ds_bpermute_b32 v3, v164, v161
	v_mov_b32_e32 v2, v187
	s_lshr_b32 s14, s34, 6
	v_mov_b32_e32 v14, v1
	v_mov_b32_e32 v15, v1
	v_mov_b32_e32 v8, v1
	v_mov_b32_e32 v9, v1
	v_mov_b32_e32 v10, v1
	v_mov_b32_e32 v11, v1
	v_mov_b32_e32 v12, v1
	v_mov_b32_e32 v13, v1
	v_mov_b32_e32 v170, 0xf149f2ca
	v_mov_b32_e32 v169, 0
	s_movk_i32 s38, 0x7f
	s_waitcnt vmcnt(0)
	v_mul_f32_e32 v0, 0xbfb8aa3b, v0
	v_exp_f32_e32 v160, v0
	s_waitcnt lgkmcnt(0)
	v_pk_add_f32 v[2:3], v[160:161], v[2:3]
	s_nop 0
	v_div_scale_f32 v0, s[0:1], v2, v2, 1.0
	v_rcp_f32_e32 v4, v0
	s_nop 0
	v_fma_f32 v5, -v0, v4, 1.0
	v_fmac_f32_e32 v4, v5, v4
	v_div_scale_f32 v5, vcc, 1.0, v2, 1.0
	v_mul_f32_e32 v6, v5, v4
	v_fma_f32 v7, -v0, v6, v5
	v_fmac_f32_e32 v6, v7, v4
	v_fma_f32 v0, -v0, v6, v5
	v_div_fmas_f32 v0, v0, v4, v6
	v_div_fixup_f32 v0, v0, v2, 1.0
	v_div_scale_f32 v2, s[0:1], v3, v3, v0
	v_rcp_f32_e32 v4, v2
	s_add_u32 s0, s48, s35
	s_addc_u32 s1, s49, 0
	s_add_u32 s0, s0, 0x13ad7000
	v_fma_f32 v5, -v2, v4, 1.0
	v_fmac_f32_e32 v4, v5, v4
	v_div_scale_f32 v5, vcc, v0, v3, v0
	v_mul_f32_e32 v6, v5, v4
	v_fma_f32 v7, -v2, v6, v5
	v_fmac_f32_e32 v6, v7, v4
	v_fma_f32 v2, -v2, v6, v5
	v_div_fmas_f32 v2, v2, v4, v6
	v_div_fixup_f32 v0, v2, v3, v0
	s_addc_u32 s1, s1, 0
	v_mov_b32_e32 v6, v1
	v_mov_b32_e32 v7, v1
	global_load_dwordx4 v[80:83], v[148:149], off
	global_load_dwordx4 v[84:87], v[148:149], off offset:32
	global_load_dwordx4 v[88:91], v[148:149], off offset:64
	global_load_dwordx4 v[92:95], v[148:149], off offset:96
	global_load_dwordx4 v[96:99], v[148:149], off offset:128
	global_load_dwordx4 v[100:103], v[148:149], off offset:160
	global_load_dwordx4 v[104:107], v[148:149], off offset:192
	global_load_dwordx4 v[108:111], v[148:149], off offset:224
	s_waitcnt vmcnt(7)
	v_pk_fma_f32 v[80:81], v[0:1], v[64:65], v[80:81] op_sel_hi:[0,1,1]
	v_pk_fma_f32 v[82:83], v[0:1], v[66:67], v[82:83] op_sel_hi:[0,1,1]
	global_store_dwordx4 v[148:149], v[80:83], off
	s_waitcnt vmcnt(7)
	v_pk_fma_f32 v[84:85], v[0:1], v[68:69], v[84:85] op_sel_hi:[0,1,1]
	v_pk_fma_f32 v[86:87], v[0:1], v[70:71], v[86:87] op_sel_hi:[0,1,1]
	global_store_dwordx4 v[148:149], v[84:87], off offset:32
	s_waitcnt vmcnt(7)
	v_pk_fma_f32 v[88:89], v[0:1], v[72:73], v[88:89] op_sel_hi:[0,1,1]
	v_pk_fma_f32 v[90:91], v[0:1], v[74:75], v[90:91] op_sel_hi:[0,1,1]
	global_store_dwordx4 v[148:149], v[88:91], off offset:64
	s_waitcnt vmcnt(7)
	v_pk_fma_f32 v[92:93], v[0:1], v[76:77], v[92:93] op_sel_hi:[0,1,1]
	v_pk_fma_f32 v[94:95], v[0:1], v[78:79], v[94:95] op_sel_hi:[0,1,1]
	global_store_dwordx4 v[148:149], v[92:95], off offset:96
	s_waitcnt vmcnt(7)
	v_pk_fma_f32 v[96:97], v[0:1], v[48:49], v[96:97] op_sel_hi:[0,1,1]
	v_pk_fma_f32 v[98:99], v[0:1], v[50:51], v[98:99] op_sel_hi:[0,1,1]
	global_store_dwordx4 v[148:149], v[96:99], off offset:128
	s_waitcnt vmcnt(7)
	v_pk_fma_f32 v[100:101], v[0:1], v[52:53], v[100:101] op_sel_hi:[0,1,1]
	v_pk_fma_f32 v[102:103], v[0:1], v[54:55], v[102:103] op_sel_hi:[0,1,1]
	global_store_dwordx4 v[148:149], v[100:103], off offset:160
	s_waitcnt vmcnt(7)
	v_pk_fma_f32 v[104:105], v[0:1], v[56:57], v[104:105] op_sel_hi:[0,1,1]
	v_pk_fma_f32 v[106:107], v[0:1], v[58:59], v[106:107] op_sel_hi:[0,1,1]
	global_store_dwordx4 v[148:149], v[104:107], off offset:192
	s_waitcnt vmcnt(7)
	v_pk_fma_f32 v[108:109], v[0:1], v[60:61], v[108:109] op_sel_hi:[0,1,1]
	v_pk_fma_f32 v[110:111], v[0:1], v[62:63], v[110:111] op_sel_hi:[0,1,1]
	global_store_dwordx4 v[148:149], v[108:111], off offset:224
	global_load_dwordx4 v[80:83], v[148:149], off offset:256
	global_load_dwordx4 v[84:87], v[148:149], off offset:288
	global_load_dwordx4 v[88:91], v[148:149], off offset:320
	global_load_dwordx4 v[92:95], v[148:149], off offset:352
	global_load_dwordx4 v[96:99], v[148:149], off offset:384
	global_load_dwordx4 v[100:103], v[148:149], off offset:416
	global_load_dwordx4 v[104:107], v[148:149], off offset:448
	global_load_dwordx4 v[108:111], v[148:149], off offset:480
	s_waitcnt vmcnt(7)
	v_pk_fma_f32 v[80:81], v[0:1], v[32:33], v[80:81] op_sel_hi:[0,1,1]
	v_pk_fma_f32 v[82:83], v[0:1], v[34:35], v[82:83] op_sel_hi:[0,1,1]
	global_store_dwordx4 v[148:149], v[80:83], off offset:256
	s_waitcnt vmcnt(7)
	v_pk_fma_f32 v[84:85], v[0:1], v[36:37], v[84:85] op_sel_hi:[0,1,1]
	v_pk_fma_f32 v[86:87], v[0:1], v[38:39], v[86:87] op_sel_hi:[0,1,1]
	global_store_dwordx4 v[148:149], v[84:87], off offset:288
	s_waitcnt vmcnt(7)
; __global__ void __launch_bounds__(256, LB2) mega(Params p, int ph_lo, int ph_hi) {
;     ...
;             for (int i4 = 0; i4 < 4; ++i4) {
;               int dv0 = d * 32 + 8 * i4 + 4 * h;
;               float4 v = *(float4*)(orow + dv0);
;               v.x += o[d][4 * i4] * gs; v.y += o[d][4 * i4 + 1] * gs; v.z += o[d][4 * i4 + 2] * gs; v.w += o[d][4 * i4 + 3] * gs;
;               *(float4*)(orow + dv0) = v;
;             }
;         }
;         {
;           const int kfirst = q0 - 511 > 0 ? (q0 - 511) >> 6 : 0;
;           CtxWin cwn{tq, posq, (q0 + 31) >> 6, sc, lutr, pos};
;           zero_o(o);
;           m = NEG; l = 0.f;
;           attn_run<128, true, false>(qf, o, m, l, P + 4096 + g * 128, NPO, nullptr, 0,
;                               (const bf16*)(ws + WS_VTWIN) + (size_t)g * 128 * L, L, kfirst, cwn, smem);
	v_pk_fma_f32 v[88:89], v[0:1], v[40:41], v[88:89] op_sel_hi:[0,1,1]
	v_pk_fma_f32 v[90:91], v[0:1], v[42:43], v[90:91] op_sel_hi:[0,1,1]
	global_store_dwordx4 v[148:149], v[88:91], off offset:320
	s_waitcnt vmcnt(7)
	v_pk_fma_f32 v[92:93], v[0:1], v[44:45], v[92:93] op_sel_hi:[0,1,1]
	v_pk_fma_f32 v[94:95], v[0:1], v[46:47], v[94:95] op_sel_hi:[0,1,1]
	global_store_dwordx4 v[148:149], v[92:95], off offset:352
	s_waitcnt vmcnt(7)
	v_pk_fma_f32 v[96:97], v[0:1], v[16:17], v[96:97] op_sel_hi:[0,1,1]
	v_pk_fma_f32 v[98:99], v[0:1], v[18:19], v[98:99] op_sel_hi:[0,1,1]
	global_store_dwordx4 v[148:149], v[96:99], off offset:384
	s_waitcnt vmcnt(7)
	v_pk_fma_f32 v[100:101], v[0:1], v[20:21], v[100:101] op_sel_hi:[0,1,1]
	v_pk_fma_f32 v[102:103], v[0:1], v[22:23], v[102:103] op_sel_hi:[0,1,1]
	global_store_dwordx4 v[148:149], v[100:103], off offset:416
	s_waitcnt vmcnt(7)
	v_pk_fma_f32 v[104:105], v[0:1], v[24:25], v[104:105] op_sel_hi:[0,1,1]
	v_pk_fma_f32 v[106:107], v[0:1], v[26:27], v[106:107] op_sel_hi:[0,1,1]
	global_store_dwordx4 v[148:149], v[104:107], off offset:448
	s_waitcnt vmcnt(7)
	v_pk_fma_f32 v[108:109], v[0:1], v[28:29], v[108:109] op_sel_hi:[0,1,1]
	v_pk_fma_f32 v[110:111], v[0:1], v[30:31], v[110:111] op_sel_hi:[0,1,1]
	global_store_dwordx4 v[148:149], v[108:111], off offset:480
	s_mov_b32 s6, 0
	s_nop 0
	v_add_u32_e32 v144, s6, v189
	v_ashrrev_i32_e32 v0, 31, v144
	v_lshrrev_b32_e32 v0, 28, v0
	v_add_u32_e32 v0, v144, v0
	v_lshrrev_b32_e32 v2, 4, v0
	v_and_b32_e32 v0, 0xffffff0, v0
	v_sub_u32_e32 v0, v144, v0
	v_mul_lo_u32 v24, v2, s73
	v_add_u32_e32 v2, 0x100, v144
	v_lshlrev_b32_e32 v25, 4, v0
	v_ashrrev_i32_e32 v0, 31, v2
	v_lshrrev_b32_e32 v0, 28, v0
	v_add_u32_e32 v0, v2, v0
	v_lshrrev_b32_e32 v3, 4, v0
	v_and_b32_e32 v0, 0xffffff0, v0
	v_sub_u32_e32 v0, v2, v0
	v_mul_lo_u32 v26, v3, s73
	v_add_u32_e32 v3, 0x200, v144
	v_lshlrev_b32_e32 v27, 4, v0
	v_ashrrev_i32_e32 v0, 31, v3
	v_lshrrev_b32_e32 v0, 28, v0
	v_add_u32_e32 v0, v3, v0
	v_lshrrev_b32_e32 v4, 4, v0
	v_and_b32_e32 v0, 0xffffff0, v0
	v_sub_u32_e32 v0, v3, v0
	v_mul_lo_u32 v28, v4, s73
	v_add_u32_e32 v4, 0x300, v144
	v_lshlrev_b32_e32 v29, 4, v0
	v_ashrrev_i32_e32 v0, 31, v4
	v_lshrrev_b32_e32 v0, 28, v0
	v_add_u32_e32 v0, v4, v0
	v_lshrrev_b32_e32 v5, 4, v0
	v_and_b32_e32 v0, 0xffffff0, v0
	v_sub_u32_e32 v0, v4, v0
	v_lshlrev_b32_e32 v31, 4, v0
	v_lshlrev_b32_e32 v0, 4, v144
	v_and_b32_e32 v0, 0x70, v0
	v_lshrrev_b32_e32 v2, 3, v2
	v_mad_u64_u32 v[18:19], s[6:7], v2, s68, v[0:1]
	v_lshrrev_b32_e32 v2, 3, v3
	v_mul_lo_u32 v30, v5, s73
	v_lshrrev_b32_e32 v5, 3, v144
	v_mad_u64_u32 v[20:21], s[6:7], v2, s68, v[0:1]
	v_lshrrev_b32_e32 v2, 3, v4
	v_mad_u64_u32 v[16:17], s[6:7], v5, s68, v[0:1]
	v_mad_u64_u32 v[22:23], s[6:7], v2, s68, v[0:1]
	s_sub_i32 s6, 0x1de1, s84
	s_max_i32 s6, s6, 0
	v_add_u32_e32 v0, v166, v165
	s_lshr_b32 s7, s6, 6
	s_and_b32 s6, s6, 0x7fffffc0
	v_subrev_u32_e32 v0, s84, v0
	v_subrev_u32_e32 v0, s6, v0
	v_add_u32_e32 v146, 0x1fa5, v0
	v_mov_b32_e32 v0, v1
	v_mov_b32_e32 v2, v1
	v_mov_b32_e32 v3, v1
	v_mov_b32_e32 v4, v1
	v_mov_b32_e32 v5, v1
	v_add_u32_e32 v147, v24, v25
	v_add_u32_e32 v151, v26, v27
	v_add_u32_e32 v160, v28, v29
	v_add_u32_e32 v161, v30, v31
	v_add_u32_e32 v165, 0x6400, v16
	v_add_u32_e32 v166, 0x6400, v18
	v_add_u32_e32 v167, 0x6400, v20
	v_add_u32_e32 v168, 0x6400, v22
	v_mov_b64_e32 v[30:31], v[14:15]
	v_mov_b64_e32 v[46:47], v[14:15]
	v_mov_b64_e32 v[62:63], v[14:15]
	v_mov_b64_e32 v[78:79], v[14:15]
	v_cmp_gt_i32_e64 s[10:11], 64, v144
	v_lshlrev_b32_e32 v145, 2, v144
	s_add_i32 s15, s7, -1
	s_or_b32 s26, s6, 59
	v_mov_b64_e32 v[28:29], v[12:13]
	v_mov_b64_e32 v[26:27], v[10:11]
	v_mov_b64_e32 v[24:25], v[8:9]
	v_mov_b64_e32 v[22:23], v[6:7]
	v_mov_b64_e32 v[20:21], v[4:5]
	v_mov_b64_e32 v[18:19], v[2:3]
	v_mov_b64_e32 v[16:17], v[0:1]
	v_mov_b64_e32 v[44:45], v[12:13]
	v_mov_b64_e32 v[42:43], v[10:11]
	v_mov_b64_e32 v[40:41], v[8:9]
	v_mov_b64_e32 v[38:39], v[6:7]
	v_mov_b64_e32 v[36:37], v[4:5]
	v_mov_b64_e32 v[34:35], v[2:3]
	v_mov_b64_e32 v[32:33], v[0:1]
	v_mov_b64_e32 v[60:61], v[12:13]
	v_mov_b64_e32 v[58:59], v[10:11]
	v_mov_b64_e32 v[56:57], v[8:9]
	v_mov_b64_e32 v[54:55], v[6:7]
	v_mov_b64_e32 v[52:53], v[4:5]
	v_mov_b64_e32 v[50:51], v[2:3]
	v_mov_b64_e32 v[48:49], v[0:1]
	v_mov_b64_e32 v[76:77], v[12:13]
	v_mov_b64_e32 v[74:75], v[10:11]
	v_mov_b64_e32 v[72:73], v[8:9]
	v_mov_b64_e32 v[70:71], v[6:7]
	v_mov_b64_e32 v[68:69], v[4:5]
	v_mov_b64_e32 v[66:67], v[2:3]
	v_mov_b64_e32 v[64:65], v[0:1]
